# speedup vs baseline: 1.0024x; 1.0014x over previous
; __device__ __forceinline__ float b2f(u16 b) { return __uint_as_float(((unsigned)b) << 16); }
; __device__ __forceinline__ float sigmoidf_(float x) { return __builtin_amdgcn_rcpf(1.f + __builtin_amdgcn_exp2f(-1.4426950408889634f * x)); }
; #define MFMA16(a, b, c) __builtin_amdgcn_mfma_f32_16x16x32_bf16(a, b, c, 0, 0, 0)
; __device__ __forceinline__ void vmix_phase(u16* V, const u16* VF, const u16* vmid, const u16* v2T, const float* v0) {
;   int tid_ = threadIdx.x; asm volatile("" : "+v"(tid_));
;   int wv = tid_ >> 6, lane = tid_ & 63, fr = lane & 15, fq = lane >> 4;
;   for (int it = blockIdx.x; it < NTOK / 16; it += gridDim.x) {
;     int tok0 = it * 16;
;     bf16x8 a = ld8(vmid + (size_t)(tok0 + fr) * 32 + fq * 8);
;     _Pragma("unroll") for (int n = 0; n < 8; ++n) {
;       int ch = wv * 128 + n * 16 + fr;
;       bf16x8 b = ld8(v2T + (size_t)ch * 32 + fq * 8);
;       f32x4 acc = {0.f, 0.f, 0.f, 0.f};
;       acc = MFMA16(a, b, acc);
;       float v0c = v0[ch];
;       _Pragma("unroll") for (int j = 0; j < 4; ++j) {
;         size_t idx = (size_t)(tok0 + fq * 4 + j) * CM + ch;
;         float v = b2f(V[idx]), vf = b2f(VF[idx]);
;         V[idx] = f2b(v + (vf - v) * sigmoidf_(v0c + acc[j]));
;       }
.LBB0_2638:
	s_and_b64 s[0:1], s[12:13], exec
	v_readlane_b32 s0, v246, 34
	v_readlane_b32 s1, v246, 35
	s_cselect_b32 s5, s97, s31
	s_cselect_b32 s4, s96, s30
	s_and_b64 vcc, exec, s[0:1]
	v_readlane_b32 s0, v247, 37
	v_readlane_b32 s1, v247, 38
	s_nop 1
	v_cndmask_b32_e64 v0, 0, 1, s[0:1]
	v_cmp_ne_u32_e64 s[16:17], 1, v0
	s_cbranch_vccz .LBB0_2681
	v_readlane_b32 s60, v248, 2
	v_readlane_b32 s61, v248, 3
	v_readlane_b32 s62, v248, 4
	v_readlane_b32 s63, v248, 5
	v_readlane_b32 s64, v248, 6
	v_readlane_b32 s65, v248, 7
	v_readlane_b32 s66, v248, 8
	v_readlane_b32 s67, v248, 9
	v_readlane_b32 s68, v248, 10
	v_readlane_b32 s69, v248, 11
	v_readlane_b32 s70, v248, 12
	v_readlane_b32 s71, v248, 13
	v_readlane_b32 s72, v248, 14
	v_readlane_b32 s73, v248, 15
	v_readlane_b32 s74, v248, 16
	v_readlane_b32 s75, v248, 17
	s_mov_b64 s[6:7], s[74:75]
	s_mov_b64 s[0:1], s[74:75]
	v_readlane_b32 s60, v248, 36
	v_readlane_b32 s72, v248, 48
	v_readlane_b32 s73, v248, 49
	s_mov_b64 s[8:9], s[72:73]
	v_mov_b32_e32 v0, v131
	s_and_b64 vcc, exec, s[16:17]
	v_readlane_b32 s10, v246, 17
	v_readlane_b32 s61, v248, 37
	v_readlane_b32 s62, v248, 38
	v_readlane_b32 s63, v248, 39
	v_readlane_b32 s64, v248, 40
	v_readlane_b32 s65, v248, 41
	v_readlane_b32 s66, v248, 42
	v_readlane_b32 s67, v248, 43
	v_readlane_b32 s68, v248, 44
	v_readlane_b32 s69, v248, 45
	v_readlane_b32 s70, v248, 46
	v_readlane_b32 s71, v248, 47
	v_readlane_b32 s74, v248, 50
	v_readlane_b32 s75, v248, 51
	s_cbranch_vccnz .LBB0_2642
	v_and_b32_e32 v42, 15, v0
	v_lshlrev_b32_e32 v1, 1, v0
	s_movk_i32 s3, 0xff80
	v_and_or_b32 v8, v1, s3, v42
	v_ashrrev_i32_e32 v9, 31, v8
	v_lshl_add_u64 v[2:3], v[8:9], 2, s[8:9]
	global_load_dword v43, v[2:3], off
	global_load_dword v44, v[2:3], off offset:64
	global_load_dword v45, v[2:3], off offset:128
	global_load_dword v46, v[2:3], off offset:192
	global_load_dword v47, v[2:3], off offset:256
	global_load_dword v48, v[2:3], off offset:320
	global_load_dword v49, v[2:3], off offset:384
	global_load_dword v50, v[2:3], off offset:448
	v_bfe_u32 v2, v0, 4, 2
	v_lshlrev_b32_e32 v128, 4, v2
	v_lshl_add_u64 v[0:1], s[6:7], 0, v[128:129]
	s_mov_b64 s[6:7], 0x34e00000
	v_lshl_add_u64 v[10:11], v[0:1], 0, s[6:7]
	v_lshl_add_u64 v[0:1], s[0:1], 0, v[128:129]
	s_mov_b64 s[0:1], 0x3f4d0000
	v_lshl_add_u64 v[0:1], v[0:1], 0, s[0:1]
	v_lshlrev_b32_e32 v51, 2, v2
	v_lshlrev_b64 v[2:3], 6, v[8:9]
	v_lshl_add_u64 v[12:13], v[0:1], 0, v[2:3]
	v_or_b32_e32 v2, 16, v8
	v_ashrrev_i32_e32 v3, 31, v2
	v_lshlrev_b64 v[2:3], 6, v[2:3]
	v_lshl_add_u64 v[14:15], v[0:1], 0, v[2:3]
	v_or_b32_e32 v2, 32, v8
	v_ashrrev_i32_e32 v3, 31, v2
	v_lshlrev_b64 v[2:3], 6, v[2:3]
	v_lshl_add_u64 v[16:17], v[0:1], 0, v[2:3]
	v_or_b32_e32 v2, 48, v8
	v_ashrrev_i32_e32 v3, 31, v2
	v_lshlrev_b64 v[2:3], 6, v[2:3]
	v_lshl_add_u64 v[18:19], v[0:1], 0, v[2:3]
	v_or_b32_e32 v2, 64, v8
	v_ashrrev_i32_e32 v3, 31, v2
	v_lshlrev_b64 v[2:3], 6, v[2:3]
	v_lshl_add_u64 v[20:21], v[0:1], 0, v[2:3]
	v_or_b32_e32 v2, 0x50, v8
	v_ashrrev_i32_e32 v3, 31, v2
	v_lshlrev_b64 v[2:3], 6, v[2:3]
	v_lshl_add_u64 v[22:23], v[0:1], 0, v[2:3]
	v_or_b32_e32 v2, 0x60, v8
	v_ashrrev_i32_e32 v3, 31, v2
	v_lshlrev_b64 v[2:3], 6, v[2:3]
	v_lshl_add_u64 v[24:25], v[0:1], 0, v[2:3]
	v_or_b32_e32 v2, 0x70, v8
	v_ashrrev_i32_e32 v3, 31, v2
	v_lshlrev_b64 v[2:3], 6, v[2:3]
	v_lshl_add_u64 v[26:27], v[0:1], 0, v[2:3]
	v_readlane_b32 s0, v247, 32
	s_add_i32 s0, s0, 0x17000
	s_mov_b32 s1, s92
	global_load_dwordx4 v[56:59], v[12:13], off
	global_load_dwordx4 v[60:63], v[14:15], off
	global_load_dwordx4 v[64:67], v[16:17], off
	global_load_dwordx4 v[68:71], v[18:19], off
	global_load_dwordx4 v[72:75], v[20:21], off
	global_load_dwordx4 v[76:79], v[22:23], off
	global_load_dwordx4 v[80:83], v[24:25], off
	global_load_dwordx4 v[84:87], v[26:27], off
	s_waitcnt vmcnt(0)
.LBB0_2641:
	s_nop 0
	v_add_u32_e32 v0, s0, v42
	v_ashrrev_i32_e32 v1, 31, v0
	v_lshlrev_b64 v[0:1], 6, v[0:1]
	v_lshl_add_u64 v[0:1], v[10:11], 0, v[0:1]
	global_load_dwordx4 v[0:3], v[0:1], off
	v_add_u32_e32 v38, s0, v51
	s_add_i32 s1, s1, s76
	v_ashrrev_i32_e32 v39, 31, v38
	v_lshlrev_b64 v[4:5], 10, v[38:39]
	v_lshl_add_u64 v[4:5], v[4:5], 0, v[8:9]
	v_lshlrev_b64 v[4:5], 1, v[4:5]
	v_lshl_add_u64 v[132:133], s[4:5], 0, v[4:5]
	v_lshl_add_u64 v[134:135], s[96:97], 0, v[4:5]
	v_add_u32_e32 v4, 1, v38
	v_ashrrev_i32_e32 v5, 31, v4
	v_lshlrev_b64 v[4:5], 10, v[4:5]
	v_lshl_add_u64 v[4:5], v[4:5], 0, v[8:9]
	v_lshlrev_b64 v[4:5], 1, v[4:5]
	v_lshl_add_u64 v[136:137], s[4:5], 0, v[4:5]
	v_lshl_add_u64 v[138:139], s[96:97], 0, v[4:5]
	v_add_u32_e32 v4, 2, v38
	v_ashrrev_i32_e32 v5, 31, v4
	v_lshlrev_b64 v[4:5], 10, v[4:5]
	v_lshl_add_u64 v[4:5], v[4:5], 0, v[8:9]
	v_lshlrev_b64 v[4:5], 1, v[4:5]
	v_lshl_add_u64 v[140:141], s[4:5], 0, v[4:5]
	v_lshl_add_u64 v[142:143], s[96:97], 0, v[4:5]
	v_add_u32_e32 v4, 3, v38
	v_ashrrev_i32_e32 v5, 31, v4
	v_lshlrev_b64 v[4:5], 10, v[4:5]
	v_lshl_add_u64 v[4:5], v[4:5], 0, v[8:9]
	v_lshlrev_b64 v[4:5], 1, v[4:5]
	v_lshl_add_u64 v[144:145], s[4:5], 0, v[4:5]
	v_lshl_add_u64 v[146:147], s[96:97], 0, v[4:5]
	global_load_ushort v194, v[132:133], off
	global_load_ushort v88, v[134:135], off
	global_load_ushort v195, v[136:137], off
	global_load_ushort v89, v[138:139], off
	global_load_ushort v196, v[140:141], off
	global_load_ushort v90, v[142:143], off
	global_load_ushort v197, v[144:145], off
	global_load_ushort v91, v[146:147], off
	global_load_ushort v198, v[132:133], off offset:32
	global_load_ushort v92, v[134:135], off offset:32
	global_load_ushort v199, v[136:137], off offset:32
	global_load_ushort v93, v[138:139], off offset:32
; __device__ __forceinline__ float b2f(u16 b) { return __uint_as_float(((unsigned)b) << 16); }
; __device__ __forceinline__ float sigmoidf_(float x) { return __builtin_amdgcn_rcpf(1.f + __builtin_amdgcn_exp2f(-1.4426950408889634f * x)); }
; #define MFMA16(a, b, c) __builtin_amdgcn_mfma_f32_16x16x32_bf16(a, b, c, 0, 0, 0)
; __device__ __forceinline__ void vmix_phase(u16* V, const u16* VF, const u16* vmid, const u16* v2T, const float* v0) {
;     ...
;   for (int it = blockIdx.x; it < NTOK / 16; it += gridDim.x) {
;     int tok0 = it * 16;
;     bf16x8 a = ld8(vmid + (size_t)(tok0 + fr) * 32 + fq * 8);
;     _Pragma("unroll") for (int n = 0; n < 8; ++n) {
;       int ch = wv * 128 + n * 16 + fr;
;       bf16x8 b = ld8(v2T + (size_t)ch * 32 + fq * 8);
;       f32x4 acc = {0.f, 0.f, 0.f, 0.f};
;       acc = MFMA16(a, b, acc);
;       float v0c = v0[ch];
;       _Pragma("unroll") for (int j = 0; j < 4; ++j) {
;         size_t idx = (size_t)(tok0 + fq * 4 + j) * CM + ch;
;         float v = b2f(V[idx]), vf = b2f(VF[idx]);
;         V[idx] = f2b(v + (vf - v) * sigmoidf_(v0c + acc[j]));
;       }
	global_load_ushort v200, v[140:141], off offset:32
	global_load_ushort v94, v[142:143], off offset:32
	global_load_ushort v201, v[144:145], off offset:32
	global_load_ushort v95, v[146:147], off offset:32
	global_load_ushort v202, v[132:133], off offset:64
	global_load_ushort v96, v[134:135], off offset:64
	global_load_ushort v203, v[136:137], off offset:64
	global_load_ushort v97, v[138:139], off offset:64
	global_load_ushort v204, v[140:141], off offset:64
	global_load_ushort v98, v[142:143], off offset:64
	global_load_ushort v205, v[144:145], off offset:64
	global_load_ushort v99, v[146:147], off offset:64
	global_load_ushort v206, v[132:133], off offset:96
	global_load_ushort v100, v[134:135], off offset:96
	global_load_ushort v207, v[136:137], off offset:96
	global_load_ushort v101, v[138:139], off offset:96
	global_load_ushort v208, v[140:141], off offset:96
	global_load_ushort v102, v[142:143], off offset:96
	global_load_ushort v209, v[144:145], off offset:96
	global_load_ushort v103, v[146:147], off offset:96
	global_load_ushort v210, v[132:133], off offset:128
	global_load_ushort v104, v[134:135], off offset:128
	global_load_ushort v211, v[136:137], off offset:128
	global_load_ushort v105, v[138:139], off offset:128
	global_load_ushort v212, v[140:141], off offset:128
	global_load_ushort v106, v[142:143], off offset:128
	global_load_ushort v213, v[144:145], off offset:128
	global_load_ushort v107, v[146:147], off offset:128
	global_load_ushort v214, v[132:133], off offset:160
	global_load_ushort v108, v[134:135], off offset:160
	global_load_ushort v215, v[136:137], off offset:160
	global_load_ushort v109, v[138:139], off offset:160
	global_load_ushort v216, v[140:141], off offset:160
	global_load_ushort v110, v[142:143], off offset:160
	global_load_ushort v217, v[144:145], off offset:160
	global_load_ushort v111, v[146:147], off offset:160
	global_load_ushort v218, v[132:133], off offset:192
	global_load_ushort v112, v[134:135], off offset:192
	global_load_ushort v219, v[136:137], off offset:192
	global_load_ushort v113, v[138:139], off offset:192
	global_load_ushort v220, v[140:141], off offset:192
	global_load_ushort v114, v[142:143], off offset:192
	global_load_ushort v221, v[144:145], off offset:192
	global_load_ushort v115, v[146:147], off offset:192
	global_load_ushort v222, v[132:133], off offset:224
	global_load_ushort v116, v[134:135], off offset:224
	global_load_ushort v223, v[136:137], off offset:224
	global_load_ushort v117, v[138:139], off offset:224
	global_load_ushort v224, v[140:141], off offset:224
	global_load_ushort v118, v[142:143], off offset:224
	global_load_ushort v225, v[144:145], off offset:224
	global_load_ushort v119, v[146:147], off offset:224
	s_waitcnt vmcnt(63)
	v_mfma_f32_16x16x32_bf16 v[148:151], v[0:3], v[56:59], 0
	v_mfma_f32_16x16x32_bf16 v[152:155], v[0:3], v[60:63], 0
	v_mfma_f32_16x16x32_bf16 v[156:159], v[0:3], v[64:67], 0
	v_mfma_f32_16x16x32_bf16 v[160:163], v[0:3], v[68:71], 0
	v_mfma_f32_16x16x32_bf16 v[164:167], v[0:3], v[72:75], 0
	v_mfma_f32_16x16x32_bf16 v[168:171], v[0:3], v[76:79], 0
	v_mfma_f32_16x16x32_bf16 v[172:175], v[0:3], v[80:83], 0
	v_mfma_f32_16x16x32_bf16 v[176:179], v[0:3], v[84:87], 0
	s_waitcnt vmcnt(56)
	v_add_f32_e32 v148, v43, v148
	v_add_f32_e32 v149, v43, v149
	v_add_f32_e32 v150, v43, v150
	v_add_f32_e32 v151, v43, v151
	v_mul_f32_e32 v148, 0xbfb8aa3b, v148
	v_mul_f32_e32 v149, 0xbfb8aa3b, v149
	v_mul_f32_e32 v150, 0xbfb8aa3b, v150
	v_mul_f32_e32 v151, 0xbfb8aa3b, v151
	v_exp_f32_e32 v148, v148
	v_exp_f32_e32 v149, v149
	v_exp_f32_e32 v150, v150
	v_exp_f32_e32 v151, v151
	v_lshlrev_b32_e32 v194, 16, v194
	v_lshlrev_b32_e32 v195, 16, v195
	v_lshlrev_b32_e32 v196, 16, v196
	v_lshlrev_b32_e32 v197, 16, v197
	v_add_f32_e32 v148, 1.0, v148
	v_add_f32_e32 v149, 1.0, v149
	v_add_f32_e32 v150, 1.0, v150
	v_add_f32_e32 v151, 1.0, v151
	v_rcp_f32_e32 v148, v148
	v_rcp_f32_e32 v149, v149
	v_rcp_f32_e32 v150, v150
	v_rcp_f32_e32 v151, v151
	v_lshlrev_b32_e32 v88, 16, v88
	v_lshlrev_b32_e32 v89, 16, v89
	v_lshlrev_b32_e32 v90, 16, v90
	v_lshlrev_b32_e32 v91, 16, v91
	v_sub_f32_e32 v88, v88, v194
	v_sub_f32_e32 v89, v89, v195
	v_sub_f32_e32 v90, v90, v196
	v_sub_f32_e32 v91, v91, v197
	v_fmac_f32_e32 v194, v148, v88
	v_fmac_f32_e32 v195, v149, v89
	v_fmac_f32_e32 v196, v150, v90
	v_fmac_f32_e32 v197, v151, v91
	v_cvt_pk_bf16_f32 v194, v194, s0
	v_cvt_pk_bf16_f32 v195, v195, s0
	v_cvt_pk_bf16_f32 v196, v196, s0
	v_cvt_pk_bf16_f32 v197, v197, s0
	global_store_short v[132:133], v194, off
	global_store_short v[136:137], v195, off
	global_store_short v[140:141], v196, off
	global_store_short v[144:145], v197, off
	s_waitcnt vmcnt(52)
	v_add_f32_e32 v152, v44, v152
	v_add_f32_e32 v153, v44, v153
	v_add_f32_e32 v154, v44, v154
	v_add_f32_e32 v155, v44, v155
	v_mul_f32_e32 v152, 0xbfb8aa3b, v152
	v_mul_f32_e32 v153, 0xbfb8aa3b, v153
	v_mul_f32_e32 v154, 0xbfb8aa3b, v154
	v_mul_f32_e32 v155, 0xbfb8aa3b, v155
	v_exp_f32_e32 v152, v152
	v_exp_f32_e32 v153, v153
	v_exp_f32_e32 v154, v154
	v_exp_f32_e32 v155, v155
	v_lshlrev_b32_e32 v198, 16, v198
	v_lshlrev_b32_e32 v199, 16, v199
	v_lshlrev_b32_e32 v200, 16, v200
	v_lshlrev_b32_e32 v201, 16, v201
	v_add_f32_e32 v152, 1.0, v152
	v_add_f32_e32 v153, 1.0, v153
	v_add_f32_e32 v154, 1.0, v154
	v_add_f32_e32 v155, 1.0, v155
	v_rcp_f32_e32 v152, v152
	v_rcp_f32_e32 v153, v153
	v_rcp_f32_e32 v154, v154
	v_rcp_f32_e32 v155, v155
	v_lshlrev_b32_e32 v92, 16, v92
	v_lshlrev_b32_e32 v93, 16, v93
	v_lshlrev_b32_e32 v94, 16, v94
	v_lshlrev_b32_e32 v95, 16, v95
	v_sub_f32_e32 v92, v92, v198
	v_sub_f32_e32 v93, v93, v199
	v_sub_f32_e32 v94, v94, v200
	v_sub_f32_e32 v95, v95, v201
	v_fmac_f32_e32 v198, v152, v92
	v_fmac_f32_e32 v199, v153, v93
	v_fmac_f32_e32 v200, v154, v94
	v_fmac_f32_e32 v201, v155, v95
	v_cvt_pk_bf16_f32 v198, v198, s0
	v_cvt_pk_bf16_f32 v199, v199, s0
	v_cvt_pk_bf16_f32 v200, v200, s0
	v_cvt_pk_bf16_f32 v201, v201, s0
	global_store_short v[132:133], v198, off offset:32
	global_store_short v[136:137], v199, off offset:32
	global_store_short v[140:141], v200, off offset:32
	global_store_short v[144:145], v201, off offset:32
	s_waitcnt vmcnt(48)
; __device__ __forceinline__ float b2f(u16 b) { return __uint_as_float(((unsigned)b) << 16); }
; __device__ __forceinline__ float sigmoidf_(float x) { return __builtin_amdgcn_rcpf(1.f + __builtin_amdgcn_exp2f(-1.4426950408889634f * x)); }
; __device__ __forceinline__ void vmix_phase(u16* V, const u16* VF, const u16* vmid, const u16* v2T, const float* v0) {
;     ...
;       _Pragma("unroll") for (int j = 0; j < 4; ++j) {
;         size_t idx = (size_t)(tok0 + fq * 4 + j) * CM + ch;
;         float v = b2f(V[idx]), vf = b2f(VF[idx]);
;         V[idx] = f2b(v + (vf - v) * sigmoidf_(v0c + acc[j]));
;       }
	v_add_f32_e32 v156, v45, v156
	v_add_f32_e32 v157, v45, v157
	v_add_f32_e32 v158, v45, v158
	v_add_f32_e32 v159, v45, v159
	v_mul_f32_e32 v156, 0xbfb8aa3b, v156
	v_mul_f32_e32 v157, 0xbfb8aa3b, v157
	v_mul_f32_e32 v158, 0xbfb8aa3b, v158
	v_mul_f32_e32 v159, 0xbfb8aa3b, v159
	v_exp_f32_e32 v156, v156
	v_exp_f32_e32 v157, v157
	v_exp_f32_e32 v158, v158
	v_exp_f32_e32 v159, v159
	v_lshlrev_b32_e32 v202, 16, v202
	v_lshlrev_b32_e32 v203, 16, v203
	v_lshlrev_b32_e32 v204, 16, v204
	v_lshlrev_b32_e32 v205, 16, v205
	v_add_f32_e32 v156, 1.0, v156
	v_add_f32_e32 v157, 1.0, v157
	v_add_f32_e32 v158, 1.0, v158
	v_add_f32_e32 v159, 1.0, v159
	v_rcp_f32_e32 v156, v156
	v_rcp_f32_e32 v157, v157
	v_rcp_f32_e32 v158, v158
	v_rcp_f32_e32 v159, v159
	v_lshlrev_b32_e32 v96, 16, v96
	v_lshlrev_b32_e32 v97, 16, v97
	v_lshlrev_b32_e32 v98, 16, v98
	v_lshlrev_b32_e32 v99, 16, v99
	v_sub_f32_e32 v96, v96, v202
	v_sub_f32_e32 v97, v97, v203
	v_sub_f32_e32 v98, v98, v204
	v_sub_f32_e32 v99, v99, v205
	v_fmac_f32_e32 v202, v156, v96
	v_fmac_f32_e32 v203, v157, v97
	v_fmac_f32_e32 v204, v158, v98
	v_fmac_f32_e32 v205, v159, v99
	v_cvt_pk_bf16_f32 v202, v202, s0
	v_cvt_pk_bf16_f32 v203, v203, s0
	v_cvt_pk_bf16_f32 v204, v204, s0
	v_cvt_pk_bf16_f32 v205, v205, s0
	global_store_short v[132:133], v202, off offset:64
	global_store_short v[136:137], v203, off offset:64
	global_store_short v[140:141], v204, off offset:64
	global_store_short v[144:145], v205, off offset:64
	s_waitcnt vmcnt(44)
	v_add_f32_e32 v160, v46, v160
	v_add_f32_e32 v161, v46, v161
	v_add_f32_e32 v162, v46, v162
	v_add_f32_e32 v163, v46, v163
	v_mul_f32_e32 v160, 0xbfb8aa3b, v160
	v_mul_f32_e32 v161, 0xbfb8aa3b, v161
	v_mul_f32_e32 v162, 0xbfb8aa3b, v162
	v_mul_f32_e32 v163, 0xbfb8aa3b, v163
	v_exp_f32_e32 v160, v160
	v_exp_f32_e32 v161, v161
	v_exp_f32_e32 v162, v162
	v_exp_f32_e32 v163, v163
	v_lshlrev_b32_e32 v206, 16, v206
	v_lshlrev_b32_e32 v207, 16, v207
	v_lshlrev_b32_e32 v208, 16, v208
	v_lshlrev_b32_e32 v209, 16, v209
	v_add_f32_e32 v160, 1.0, v160
	v_add_f32_e32 v161, 1.0, v161
	v_add_f32_e32 v162, 1.0, v162
	v_add_f32_e32 v163, 1.0, v163
	v_rcp_f32_e32 v160, v160
	v_rcp_f32_e32 v161, v161
	v_rcp_f32_e32 v162, v162
	v_rcp_f32_e32 v163, v163
	v_lshlrev_b32_e32 v100, 16, v100
	v_lshlrev_b32_e32 v101, 16, v101
	v_lshlrev_b32_e32 v102, 16, v102
	v_lshlrev_b32_e32 v103, 16, v103
	v_sub_f32_e32 v100, v100, v206
	v_sub_f32_e32 v101, v101, v207
	v_sub_f32_e32 v102, v102, v208
	v_sub_f32_e32 v103, v103, v209
	v_fmac_f32_e32 v206, v160, v100
	v_fmac_f32_e32 v207, v161, v101
	v_fmac_f32_e32 v208, v162, v102
	v_fmac_f32_e32 v209, v163, v103
	v_cvt_pk_bf16_f32 v206, v206, s0
	v_cvt_pk_bf16_f32 v207, v207, s0
	v_cvt_pk_bf16_f32 v208, v208, s0
	v_cvt_pk_bf16_f32 v209, v209, s0
	global_store_short v[132:133], v206, off offset:96
	global_store_short v[136:137], v207, off offset:96
	global_store_short v[140:141], v208, off offset:96
	global_store_short v[144:145], v209, off offset:96
	s_waitcnt vmcnt(40)
	v_add_f32_e32 v164, v47, v164
	v_add_f32_e32 v165, v47, v165
	v_add_f32_e32 v166, v47, v166
	v_add_f32_e32 v167, v47, v167
	v_mul_f32_e32 v164, 0xbfb8aa3b, v164
	v_mul_f32_e32 v165, 0xbfb8aa3b, v165
	v_mul_f32_e32 v166, 0xbfb8aa3b, v166
	v_mul_f32_e32 v167, 0xbfb8aa3b, v167
	v_exp_f32_e32 v164, v164
	v_exp_f32_e32 v165, v165
	v_exp_f32_e32 v166, v166
	v_exp_f32_e32 v167, v167
	v_lshlrev_b32_e32 v210, 16, v210
	v_lshlrev_b32_e32 v211, 16, v211
	v_lshlrev_b32_e32 v212, 16, v212
	v_lshlrev_b32_e32 v213, 16, v213
	v_add_f32_e32 v164, 1.0, v164
	v_add_f32_e32 v165, 1.0, v165
	v_add_f32_e32 v166, 1.0, v166
	v_add_f32_e32 v167, 1.0, v167
	v_rcp_f32_e32 v164, v164
	v_rcp_f32_e32 v165, v165
	v_rcp_f32_e32 v166, v166
	v_rcp_f32_e32 v167, v167
	v_lshlrev_b32_e32 v104, 16, v104
	v_lshlrev_b32_e32 v105, 16, v105
	v_lshlrev_b32_e32 v106, 16, v106
	v_lshlrev_b32_e32 v107, 16, v107
	v_sub_f32_e32 v104, v104, v210
	v_sub_f32_e32 v105, v105, v211
	v_sub_f32_e32 v106, v106, v212
	v_sub_f32_e32 v107, v107, v213
	v_fmac_f32_e32 v210, v164, v104
	v_fmac_f32_e32 v211, v165, v105
	v_fmac_f32_e32 v212, v166, v106
	v_fmac_f32_e32 v213, v167, v107
	v_cvt_pk_bf16_f32 v210, v210, s0
	v_cvt_pk_bf16_f32 v211, v211, s0
	v_cvt_pk_bf16_f32 v212, v212, s0
	v_cvt_pk_bf16_f32 v213, v213, s0
	global_store_short v[132:133], v210, off offset:128
	global_store_short v[136:137], v211, off offset:128
	global_store_short v[140:141], v212, off offset:128
	global_store_short v[144:145], v213, off offset:128
	s_waitcnt vmcnt(36)
; __device__ __forceinline__ float b2f(u16 b) { return __uint_as_float(((unsigned)b) << 16); }
; __device__ __forceinline__ float sigmoidf_(float x) { return __builtin_amdgcn_rcpf(1.f + __builtin_amdgcn_exp2f(-1.4426950408889634f * x)); }
; __device__ __forceinline__ void vmix_phase(u16* V, const u16* VF, const u16* vmid, const u16* v2T, const float* v0) {
;     ...
;   for (int it = blockIdx.x; it < NTOK / 16; it += gridDim.x) {
;     ...
;       _Pragma("unroll") for (int j = 0; j < 4; ++j) {
;         size_t idx = (size_t)(tok0 + fq * 4 + j) * CM + ch;
;         float v = b2f(V[idx]), vf = b2f(VF[idx]);
;         V[idx] = f2b(v + (vf - v) * sigmoidf_(v0c + acc[j]));
;       }
	v_add_f32_e32 v168, v48, v168
	v_add_f32_e32 v169, v48, v169
	v_add_f32_e32 v170, v48, v170
	v_add_f32_e32 v171, v48, v171
	v_mul_f32_e32 v168, 0xbfb8aa3b, v168
	v_mul_f32_e32 v169, 0xbfb8aa3b, v169
	v_mul_f32_e32 v170, 0xbfb8aa3b, v170
	v_mul_f32_e32 v171, 0xbfb8aa3b, v171
	v_exp_f32_e32 v168, v168
	v_exp_f32_e32 v169, v169
	v_exp_f32_e32 v170, v170
	v_exp_f32_e32 v171, v171
	v_lshlrev_b32_e32 v214, 16, v214
	v_lshlrev_b32_e32 v215, 16, v215
	v_lshlrev_b32_e32 v216, 16, v216
	v_lshlrev_b32_e32 v217, 16, v217
	v_add_f32_e32 v168, 1.0, v168
	v_add_f32_e32 v169, 1.0, v169
	v_add_f32_e32 v170, 1.0, v170
	v_add_f32_e32 v171, 1.0, v171
	v_rcp_f32_e32 v168, v168
	v_rcp_f32_e32 v169, v169
	v_rcp_f32_e32 v170, v170
	v_rcp_f32_e32 v171, v171
	v_lshlrev_b32_e32 v108, 16, v108
	v_lshlrev_b32_e32 v109, 16, v109
	v_lshlrev_b32_e32 v110, 16, v110
	v_lshlrev_b32_e32 v111, 16, v111
	v_sub_f32_e32 v108, v108, v214
	v_sub_f32_e32 v109, v109, v215
	v_sub_f32_e32 v110, v110, v216
	v_sub_f32_e32 v111, v111, v217
	v_fmac_f32_e32 v214, v168, v108
	v_fmac_f32_e32 v215, v169, v109
	v_fmac_f32_e32 v216, v170, v110
	v_fmac_f32_e32 v217, v171, v111
	v_cvt_pk_bf16_f32 v214, v214, s0
	v_cvt_pk_bf16_f32 v215, v215, s0
	v_cvt_pk_bf16_f32 v216, v216, s0
	v_cvt_pk_bf16_f32 v217, v217, s0
	global_store_short v[132:133], v214, off offset:160
	global_store_short v[136:137], v215, off offset:160
	global_store_short v[140:141], v216, off offset:160
	global_store_short v[144:145], v217, off offset:160
	s_waitcnt vmcnt(32)
	v_add_f32_e32 v172, v49, v172
	v_add_f32_e32 v173, v49, v173
	v_add_f32_e32 v174, v49, v174
	v_add_f32_e32 v175, v49, v175
	v_mul_f32_e32 v172, 0xbfb8aa3b, v172
	v_mul_f32_e32 v173, 0xbfb8aa3b, v173
	v_mul_f32_e32 v174, 0xbfb8aa3b, v174
	v_mul_f32_e32 v175, 0xbfb8aa3b, v175
	v_exp_f32_e32 v172, v172
	v_exp_f32_e32 v173, v173
	v_exp_f32_e32 v174, v174
	v_exp_f32_e32 v175, v175
	v_lshlrev_b32_e32 v218, 16, v218
	v_lshlrev_b32_e32 v219, 16, v219
	v_lshlrev_b32_e32 v220, 16, v220
	v_lshlrev_b32_e32 v221, 16, v221
	v_add_f32_e32 v172, 1.0, v172
	v_add_f32_e32 v173, 1.0, v173
	v_add_f32_e32 v174, 1.0, v174
	v_add_f32_e32 v175, 1.0, v175
	v_rcp_f32_e32 v172, v172
	v_rcp_f32_e32 v173, v173
	v_rcp_f32_e32 v174, v174
	v_rcp_f32_e32 v175, v175
	v_lshlrev_b32_e32 v112, 16, v112
	v_lshlrev_b32_e32 v113, 16, v113
	v_lshlrev_b32_e32 v114, 16, v114
	v_lshlrev_b32_e32 v115, 16, v115
	v_sub_f32_e32 v112, v112, v218
	v_sub_f32_e32 v113, v113, v219
	v_sub_f32_e32 v114, v114, v220
	v_sub_f32_e32 v115, v115, v221
	v_fmac_f32_e32 v218, v172, v112
	v_fmac_f32_e32 v219, v173, v113
	v_fmac_f32_e32 v220, v174, v114
	v_fmac_f32_e32 v221, v175, v115
	v_cvt_pk_bf16_f32 v218, v218, s0
	v_cvt_pk_bf16_f32 v219, v219, s0
	v_cvt_pk_bf16_f32 v220, v220, s0
	v_cvt_pk_bf16_f32 v221, v221, s0
	global_store_short v[132:133], v218, off offset:192
	global_store_short v[136:137], v219, off offset:192
	global_store_short v[140:141], v220, off offset:192
	global_store_short v[144:145], v221, off offset:192
	s_waitcnt vmcnt(28)
	v_add_f32_e32 v176, v50, v176
	v_add_f32_e32 v177, v50, v177
	v_add_f32_e32 v178, v50, v178
	v_add_f32_e32 v179, v50, v179
	v_mul_f32_e32 v176, 0xbfb8aa3b, v176
	v_mul_f32_e32 v177, 0xbfb8aa3b, v177
	v_mul_f32_e32 v178, 0xbfb8aa3b, v178
	v_mul_f32_e32 v179, 0xbfb8aa3b, v179
	v_exp_f32_e32 v176, v176
	v_exp_f32_e32 v177, v177
	v_exp_f32_e32 v178, v178
	v_exp_f32_e32 v179, v179
	v_lshlrev_b32_e32 v222, 16, v222
	v_lshlrev_b32_e32 v223, 16, v223
	v_lshlrev_b32_e32 v224, 16, v224
	v_lshlrev_b32_e32 v225, 16, v225
	v_add_f32_e32 v176, 1.0, v176
	v_add_f32_e32 v177, 1.0, v177
	v_add_f32_e32 v178, 1.0, v178
	v_add_f32_e32 v179, 1.0, v179
	v_rcp_f32_e32 v176, v176
	v_rcp_f32_e32 v177, v177
	v_rcp_f32_e32 v178, v178
	v_rcp_f32_e32 v179, v179
	v_lshlrev_b32_e32 v116, 16, v116
	v_lshlrev_b32_e32 v117, 16, v117
	v_lshlrev_b32_e32 v118, 16, v118
	v_lshlrev_b32_e32 v119, 16, v119
	v_sub_f32_e32 v116, v116, v222
	v_sub_f32_e32 v117, v117, v223
	v_sub_f32_e32 v118, v118, v224
	v_sub_f32_e32 v119, v119, v225
	v_fmac_f32_e32 v222, v176, v116
	v_fmac_f32_e32 v223, v177, v117
	v_fmac_f32_e32 v224, v178, v118
	v_fmac_f32_e32 v225, v179, v119
	v_cvt_pk_bf16_f32 v222, v222, s0
	v_cvt_pk_bf16_f32 v223, v223, s0
	v_cvt_pk_bf16_f32 v224, v224, s0
	v_cvt_pk_bf16_f32 v225, v225, s0
	global_store_short v[132:133], v222, off offset:224
	global_store_short v[136:137], v223, off offset:224
	global_store_short v[140:141], v224, off offset:224
	global_store_short v[144:145], v225, off offset:224
	s_sub_i32 s0, s0, s10
	s_cmpk_lt_i32 s1, 0x1800
	s_cbranch_scc1 .LBB0_2641
